# main residual GEMM K-loop: scalar-base LDS-DMA loads, A-fragment LDS base in one persistent VGPR (no VALU in load segments), on top of the same change in the Up GEMM
# speedup vs baseline: 1.0103x; 1.0041x over previous
; #define PG8_STAGE(bufoff, gbase, voff) do { _Pragma("unroll") for (int _i = 0; _i < 2; ++_i) \
;         __builtin_amdgcn_global_load_lds((const unsigned*)((const char*)(gbase) + (voff)[_i]), (LAS unsigned*)(lds + (bufoff) + ldsw + _i * 8192), 16, 0, 0); } while (0)
; #define PG8_LDA(dst, b, h) do { _Pragma("unroll") for (int m = 0; m < 4; ++m) _Pragma("unroll") for (int k = 0; k < 2; ++k) dst[m][k] = *(const LAS bf16x8*)(lds + PG8_SA(b, h) + aoff + m * 2048 + k * 1024); } while (0)
; #define PG8_LDB(dst, b, h) do { _Pragma("unroll") for (int n = 0; n < 2; ++n) _Pragma("unroll") for (int k = 0; k < 2; ++k) dst[n][k] = *(const LAS bf16x8*)(lds + PG8_SB(b, h) + boff + n * 2048 + k * 1024); } while (0)
; #define PG8_MMA(ai, bj, At, Bt) do { __builtin_amdgcn_s_setprio(1); _Pragma("unroll") for (int m = 0; m < 4; ++m) _Pragma("unroll") for (int n = 0; n < 2; ++n) _Pragma("unroll") for (int k = 0; k < 2; ++k) \
;         acc[ai][bj][m][n] = __builtin_amdgcn_mfma_f32_16x16x32_bf16(Bt[n][k], At[m][k], acc[ai][bj][m][n], 0, 0, 0); __builtin_amdgcn_s_setprio(0); } while (0)
; #define PG8_WAIT_V(n) asm volatile("s_waitcnt vmcnt(" #n ")" ::: "memory")
; #define PG8_WAIT_L(n) asm volatile("s_waitcnt lgkmcnt(" #n ")" ::: "memory")
; #define PG8_BAR __builtin_amdgcn_s_barrier()
; #define PG8_SCHED __builtin_amdgcn_sched_barrier(0)
; template <class Epi, class Sched>
; __device__ __forceinline__ void gemm_phase(LAS unsigned char* lds, const Gemm g, const Sched& S, const Epi& E) {
;     ...
;         for (int t = 0; t < nt; t += 2) {
;             const bool last = (t == nt - 2);
;             const char* a1 = cA + (size_t)(t + 1) * kstep;
;             const char* a2 = last ? nA : cA + (size_t)(t + 2) * kstep; const char* b2 = last ? nB : cB + (size_t)(t + 2) * kstep;
;             const char* a3 = a2 + kstep; const char* b3 = b2 + kstep;
;             PG8_LDB(B0, 0, 0); PG8_LDB(B1, 0, 1); PG8_SCHED; PG8_LDA(At, 0, 0); PG8_STAGE(PG8_SA(1, 1), a1 + hstepA, voffA);
;             PG8_WAIT_V(8); PG8_WAIT_L(0); PG8_BAR; PG8_MMA(0, 0, At, B0); PG8_MMA(0, 1, At, B1); PG8_BAR; PG8_SCHED;
;             PG8_LDA(At, 0, 1); PG8_STAGE(PG8_SB(0, 0), b2, voffB); PG8_STAGE(PG8_SB(0, 1), b2 + hstepB, voffB); PG8_STAGE(PG8_SA(0, 0), a2, voffA);
;             PG8_WAIT_V(8); PG8_WAIT_L(0); PG8_BAR; PG8_MMA(1, 0, At, B0); PG8_MMA(1, 1, At, B1); PG8_BAR; PG8_SCHED;
.LBB0_597:
	s_add_u32 s18, s18, 0x80
	s_addc_u32 s19, s19, 0
	s_add_u32 s86, s86, 0x100
	s_addc_u32 s87, s87, 0
	s_mov_b32 s20, 0
	v_add_u32_e32 v255, 0x10000, v146
.LBB0_598:
	s_add_i32 vcc_lo, s20, 2
	s_add_u32 s90, s18, 0x80
	s_addc_u32 s21, s19, 0
	s_add_i32 s92, 0, 0x10000
	s_cmp_eq_u32 s43, s20
	s_cselect_b32 s21, s37, s21
	s_cselect_b32 s20, s36, s90
	s_cselect_b32 s91, s71, s87
	s_cselect_b32 s90, s70, s86
	s_add_i32 s93, 0, 0x14000
	ds_read_b128 v[142:145], v255
	ds_read_b128 v[150:153], v255 offset:1024
	ds_read_b128 v[154:157], v255 offset:2048
	ds_read_b128 v[158:161], v255 offset:3072
	ds_read_b128 v[162:165], v255 offset:16384
	ds_read_b128 v[166:169], v255 offset:17408
	ds_read_b128 v[170:173], v255 offset:18432
	ds_read_b128 v[190:193], v255 offset:19456
	s_add_i32 m0, s35, 0xc000
	ds_read_b128 v[194:197], v148
	ds_read_b128 v[198:201], v148 offset:1024
	ds_read_b128 v[202:205], v148 offset:2048
	ds_read_b128 v[206:209], v148 offset:3072
	ds_read_b128 v[218:221], v148 offset:4096
	ds_read_b128 v[222:225], v148 offset:5120
	ds_read_b128 v[226:229], v148 offset:6144
	ds_read_b128 v[230:233], v148 offset:7168
	global_load_lds_dwordx4 v138, s[18:19]
	s_add_i32 m0, s35, 0xe000
	s_nop 0
	global_load_lds_dwordx4 v140, s[18:19]
	s_waitcnt vmcnt(8)
	s_waitcnt lgkmcnt(0)
	s_barrier
	s_setprio 1
	s_waitcnt lgkmcnt(0)
	v_mfma_f32_16x16x32_bf16 v[114:117], v[142:145], v[194:197], v[114:117]
	v_mfma_f32_16x16x32_bf16 v[118:121], v[154:157], v[194:197], v[118:121]
	v_mfma_f32_16x16x32_bf16 v[94:97], v[142:145], v[202:205], v[94:97]
	v_mfma_f32_16x16x32_bf16 v[98:101], v[154:157], v[202:205], v[98:101]
	v_mfma_f32_16x16x32_bf16 v[62:65], v[142:145], v[218:221], v[62:65]
	v_mfma_f32_16x16x32_bf16 v[66:69], v[154:157], v[218:221], v[66:69]
	v_mfma_f32_16x16x32_bf16 v[22:25], v[142:145], v[226:229], v[22:25]
	v_mfma_f32_16x16x32_bf16 v[34:37], v[154:157], v[226:229], v[34:37]
	v_mfma_f32_16x16x32_bf16 v[114:117], v[150:153], v[198:201], v[114:117]
	v_mfma_f32_16x16x32_bf16 v[118:121], v[158:161], v[198:201], v[118:121]
	v_mfma_f32_16x16x32_bf16 v[94:97], v[150:153], v[206:209], v[94:97]
	v_mfma_f32_16x16x32_bf16 v[98:101], v[158:161], v[206:209], v[98:101]
	v_mfma_f32_16x16x32_bf16 v[62:65], v[150:153], v[222:225], v[62:65]
	v_mfma_f32_16x16x32_bf16 v[66:69], v[158:161], v[222:225], v[66:69]
	v_mfma_f32_16x16x32_bf16 v[22:25], v[150:153], v[230:233], v[22:25]
	v_mfma_f32_16x16x32_bf16 v[34:37], v[158:161], v[230:233], v[34:37]
	s_setprio 0
	s_setprio 1
	v_mfma_f32_16x16x32_bf16 v[122:125], v[162:165], v[194:197], v[122:125]
	v_mfma_f32_16x16x32_bf16 v[126:129], v[170:173], v[194:197], v[126:129]
	v_mfma_f32_16x16x32_bf16 v[102:105], v[162:165], v[202:205], v[102:105]
	v_mfma_f32_16x16x32_bf16 v[106:109], v[170:173], v[202:205], v[106:109]
	v_mfma_f32_16x16x32_bf16 v[70:73], v[162:165], v[218:221], v[70:73]
	v_mfma_f32_16x16x32_bf16 v[78:81], v[170:173], v[218:221], v[78:81]
	v_mfma_f32_16x16x32_bf16 v[38:41], v[162:165], v[226:229], v[38:41]
	v_mfma_f32_16x16x32_bf16 v[46:49], v[170:173], v[226:229], v[46:49]
	v_mfma_f32_16x16x32_bf16 v[122:125], v[166:169], v[198:201], v[122:125]
	v_mfma_f32_16x16x32_bf16 v[126:129], v[190:193], v[198:201], v[126:129]
	v_mfma_f32_16x16x32_bf16 v[102:105], v[166:169], v[206:209], v[102:105]
	v_mfma_f32_16x16x32_bf16 v[106:109], v[190:193], v[206:209], v[106:109]
	v_mfma_f32_16x16x32_bf16 v[70:73], v[166:169], v[222:225], v[70:73]
	v_mfma_f32_16x16x32_bf16 v[78:81], v[190:193], v[222:225], v[78:81]
	v_mfma_f32_16x16x32_bf16 v[38:41], v[166:169], v[230:233], v[38:41]
	v_mfma_f32_16x16x32_bf16 v[46:49], v[190:193], v[230:233], v[46:49]
	s_setprio 0
	s_barrier
	s_add_i32 s92, s92, s34
	s_add_u32 s98, s90, 0x80
	s_addc_u32 s99, s91, 0
	s_add_u32 s100, s20, 0x80
	s_addc_u32 s101, s21, 0
	s_mov_b32 m0, s92
	ds_read_b128 v[194:197], v148 offset:16384
	ds_read_b128 v[198:201], v148 offset:17408
	ds_read_b128 v[202:205], v148 offset:18432
	ds_read_b128 v[206:209], v148 offset:19456
	ds_read_b128 v[218:221], v148 offset:20480
	ds_read_b128 v[222:225], v148 offset:21504
	ds_read_b128 v[226:229], v148 offset:22528
	ds_read_b128 v[230:233], v148 offset:23552
	global_load_lds_dwordx4 v132, s[90:91]
	s_add_i32 m0, s92, 0x2000
	s_add_i32 s92, s93, s34
	global_load_lds_dwordx4 v136, s[90:91]
	s_add_u32 s90, s90, s29
	s_addc_u32 s91, s91, 0
	s_mov_b32 m0, s92
	s_nop 0
	global_load_lds_dwordx4 v132, s[90:91]
	s_add_i32 m0, s92, 0x2000
	s_nop 0
	global_load_lds_dwordx4 v136, s[90:91]
	s_mov_b32 m0, s35
	s_nop 0
	global_load_lds_dwordx4 v130, s[20:21]
	s_mov_b32 m0, s8
	s_nop 0
	global_load_lds_dwordx4 v134, s[20:21]
	s_waitcnt vmcnt(8)
	s_waitcnt lgkmcnt(0)
	s_barrier
; #define PG8_STAGE(bufoff, gbase, voff) do { _Pragma("unroll") for (int _i = 0; _i < 2; ++_i) \
;         __builtin_amdgcn_global_load_lds((const unsigned*)((const char*)(gbase) + (voff)[_i]), (LAS unsigned*)(lds + (bufoff) + ldsw + _i * 8192), 16, 0, 0); } while (0)
; #define PG8_LDA(dst, b, h) do { _Pragma("unroll") for (int m = 0; m < 4; ++m) _Pragma("unroll") for (int k = 0; k < 2; ++k) dst[m][k] = *(const LAS bf16x8*)(lds + PG8_SA(b, h) + aoff + m * 2048 + k * 1024); } while (0)
; #define PG8_LDB(dst, b, h) do { _Pragma("unroll") for (int n = 0; n < 2; ++n) _Pragma("unroll") for (int k = 0; k < 2; ++k) dst[n][k] = *(const LAS bf16x8*)(lds + PG8_SB(b, h) + boff + n * 2048 + k * 1024); } while (0)
; #define PG8_MMA(ai, bj, At, Bt) do { __builtin_amdgcn_s_setprio(1); _Pragma("unroll") for (int m = 0; m < 4; ++m) _Pragma("unroll") for (int n = 0; n < 2; ++n) _Pragma("unroll") for (int k = 0; k < 2; ++k) \
;         acc[ai][bj][m][n] = __builtin_amdgcn_mfma_f32_16x16x32_bf16(Bt[n][k], At[m][k], acc[ai][bj][m][n], 0, 0, 0); __builtin_amdgcn_s_setprio(0); } while (0)
; #define PG8_WAIT_V(n) asm volatile("s_waitcnt vmcnt(" #n ")" ::: "memory")
; #define PG8_WAIT_L(n) asm volatile("s_waitcnt lgkmcnt(" #n ")" ::: "memory")
; #define PG8_BAR __builtin_amdgcn_s_barrier()
; #define PG8_SCHED __builtin_amdgcn_sched_barrier(0)
; template <class Epi, class Sched>
; __device__ __forceinline__ void gemm_phase(LAS unsigned char* lds, const Gemm g, const Sched& S, const Epi& E) {
;     ...
;             PG8_WAIT_V(8); PG8_WAIT_L(0); PG8_BAR; PG8_MMA(1, 0, At, B0); PG8_MMA(1, 1, At, B1); PG8_BAR; PG8_SCHED;
;             PG8_LDB(B0, 1, 0); PG8_LDB(B1, 1, 1); PG8_SCHED; PG8_LDA(At, 1, 0); PG8_STAGE(PG8_SA(0, 1), a2 + hstepA, voffA);
;             PG8_WAIT_V(8); PG8_WAIT_L(0); PG8_BAR; PG8_MMA(0, 0, At, B0); PG8_MMA(0, 1, At, B1); PG8_BAR; PG8_SCHED;
	s_setprio 1
	s_waitcnt lgkmcnt(0)
	v_mfma_f32_16x16x32_bf16 v[14:17], v[142:145], v[194:197], v[14:17]
	v_mfma_f32_16x16x32_bf16 v[26:29], v[154:157], v[194:197], v[26:29]
	v_mfma_f32_16x16x32_bf16 v[74:77], v[142:145], v[202:205], v[74:77]
	v_mfma_f32_16x16x32_bf16 v[82:85], v[154:157], v[202:205], v[82:85]
	v_mfma_f32_16x16x32_bf16 v[42:45], v[142:145], v[218:221], v[42:45]
	v_mfma_f32_16x16x32_bf16 v[50:53], v[154:157], v[218:221], v[50:53]
	v_mfma_f32_16x16x32_bf16 v[2:5], v[142:145], v[226:229], v[2:5]
	v_mfma_f32_16x16x32_bf16 v[6:9], v[154:157], v[226:229], v[6:9]
	v_mfma_f32_16x16x32_bf16 v[14:17], v[150:153], v[198:201], v[14:17]
	v_mfma_f32_16x16x32_bf16 v[26:29], v[158:161], v[198:201], v[26:29]
	v_mfma_f32_16x16x32_bf16 v[74:77], v[150:153], v[206:209], v[74:77]
	v_mfma_f32_16x16x32_bf16 v[82:85], v[158:161], v[206:209], v[82:85]
	v_mfma_f32_16x16x32_bf16 v[42:45], v[150:153], v[222:225], v[42:45]
	v_mfma_f32_16x16x32_bf16 v[50:53], v[158:161], v[222:225], v[50:53]
	v_mfma_f32_16x16x32_bf16 v[2:5], v[150:153], v[230:233], v[2:5]
	v_mfma_f32_16x16x32_bf16 v[6:9], v[158:161], v[230:233], v[6:9]
	s_setprio 0
	s_setprio 1
	v_mfma_f32_16x16x32_bf16 v[30:33], v[162:165], v[194:197], v[30:33]
	v_mfma_f32_16x16x32_bf16 v[110:113], v[170:173], v[194:197], v[110:113]
	v_mfma_f32_16x16x32_bf16 v[86:89], v[162:165], v[202:205], v[86:89]
	v_mfma_f32_16x16x32_bf16 v[90:93], v[170:173], v[202:205], v[90:93]
	v_mfma_f32_16x16x32_bf16 v[54:57], v[162:165], v[218:221], v[54:57]
	v_mfma_f32_16x16x32_bf16 v[58:61], v[170:173], v[218:221], v[58:61]
	v_mfma_f32_16x16x32_bf16 v[10:13], v[162:165], v[226:229], v[10:13]
	v_mfma_f32_16x16x32_bf16 v[18:21], v[170:173], v[226:229], v[18:21]
	v_mfma_f32_16x16x32_bf16 v[30:33], v[166:169], v[198:201], v[30:33]
	v_mfma_f32_16x16x32_bf16 v[110:113], v[190:193], v[198:201], v[110:113]
	v_mfma_f32_16x16x32_bf16 v[86:89], v[166:169], v[206:209], v[86:89]
	v_mfma_f32_16x16x32_bf16 v[90:93], v[190:193], v[206:209], v[90:93]
	v_mfma_f32_16x16x32_bf16 v[54:57], v[166:169], v[222:225], v[54:57]
	v_mfma_f32_16x16x32_bf16 v[58:61], v[190:193], v[222:225], v[58:61]
	v_mfma_f32_16x16x32_bf16 v[10:13], v[166:169], v[230:233], v[10:13]
	v_mfma_f32_16x16x32_bf16 v[18:21], v[190:193], v[230:233], v[18:21]
	s_setprio 0
	s_barrier
	ds_read_b128 v[142:145], v255 offset:32768
	ds_read_b128 v[150:153], v255 offset:33792
	ds_read_b128 v[154:157], v255 offset:34816
	ds_read_b128 v[158:161], v255 offset:35840
	ds_read_b128 v[162:165], v255 offset:49152
	ds_read_b128 v[166:169], v255 offset:50176
	ds_read_b128 v[170:173], v255 offset:51200
	ds_read_b128 v[190:193], v255 offset:52224
	s_add_u32 s20, s20, s80
	s_addc_u32 s21, s21, 0
	s_mov_b32 m0, s9
	ds_read_b128 v[194:197], v148 offset:32768
	ds_read_b128 v[198:201], v148 offset:33792
	ds_read_b128 v[202:205], v148 offset:34816
	ds_read_b128 v[206:209], v148 offset:35840
	ds_read_b128 v[218:221], v148 offset:36864
	ds_read_b128 v[222:225], v148 offset:37888
	ds_read_b128 v[226:229], v148 offset:38912
	ds_read_b128 v[230:233], v148 offset:39936
	global_load_lds_dwordx4 v130, s[20:21]
	s_mov_b32 m0, s40
	s_nop 0
	global_load_lds_dwordx4 v134, s[20:21]
	s_waitcnt vmcnt(8)
	s_waitcnt lgkmcnt(0)
	s_barrier
	s_setprio 1
	s_waitcnt lgkmcnt(0)
	v_mfma_f32_16x16x32_bf16 v[114:117], v[142:145], v[194:197], v[114:117]
	v_mfma_f32_16x16x32_bf16 v[118:121], v[154:157], v[194:197], v[118:121]
	v_mfma_f32_16x16x32_bf16 v[94:97], v[142:145], v[202:205], v[94:97]
	v_mfma_f32_16x16x32_bf16 v[98:101], v[154:157], v[202:205], v[98:101]
	v_mfma_f32_16x16x32_bf16 v[62:65], v[142:145], v[218:221], v[62:65]
	v_mfma_f32_16x16x32_bf16 v[66:69], v[154:157], v[218:221], v[66:69]
	v_mfma_f32_16x16x32_bf16 v[22:25], v[142:145], v[226:229], v[22:25]
	v_mfma_f32_16x16x32_bf16 v[34:37], v[154:157], v[226:229], v[34:37]
	v_mfma_f32_16x16x32_bf16 v[114:117], v[150:153], v[198:201], v[114:117]
	v_mfma_f32_16x16x32_bf16 v[118:121], v[158:161], v[198:201], v[118:121]
	v_mfma_f32_16x16x32_bf16 v[94:97], v[150:153], v[206:209], v[94:97]
	v_mfma_f32_16x16x32_bf16 v[98:101], v[158:161], v[206:209], v[98:101]
	v_mfma_f32_16x16x32_bf16 v[62:65], v[150:153], v[222:225], v[62:65]
	v_mfma_f32_16x16x32_bf16 v[66:69], v[158:161], v[222:225], v[66:69]
	v_mfma_f32_16x16x32_bf16 v[22:25], v[150:153], v[230:233], v[22:25]
	v_mfma_f32_16x16x32_bf16 v[34:37], v[158:161], v[230:233], v[34:37]
	s_setprio 0
	s_setprio 1
	v_mfma_f32_16x16x32_bf16 v[122:125], v[162:165], v[194:197], v[122:125]
	v_mfma_f32_16x16x32_bf16 v[126:129], v[170:173], v[194:197], v[126:129]
	v_mfma_f32_16x16x32_bf16 v[102:105], v[162:165], v[202:205], v[102:105]
	v_mfma_f32_16x16x32_bf16 v[106:109], v[170:173], v[202:205], v[106:109]
	v_mfma_f32_16x16x32_bf16 v[70:73], v[162:165], v[218:221], v[70:73]
	v_mfma_f32_16x16x32_bf16 v[78:81], v[170:173], v[218:221], v[78:81]
	v_mfma_f32_16x16x32_bf16 v[38:41], v[162:165], v[226:229], v[38:41]
	v_mfma_f32_16x16x32_bf16 v[46:49], v[170:173], v[226:229], v[46:49]
	v_mfma_f32_16x16x32_bf16 v[122:125], v[166:169], v[198:201], v[122:125]
	v_mfma_f32_16x16x32_bf16 v[126:129], v[190:193], v[198:201], v[126:129]
	v_mfma_f32_16x16x32_bf16 v[102:105], v[166:169], v[206:209], v[102:105]
	v_mfma_f32_16x16x32_bf16 v[106:109], v[190:193], v[206:209], v[106:109]
	v_mfma_f32_16x16x32_bf16 v[70:73], v[166:169], v[222:225], v[70:73]
	v_mfma_f32_16x16x32_bf16 v[78:81], v[190:193], v[222:225], v[78:81]
	v_mfma_f32_16x16x32_bf16 v[38:41], v[166:169], v[230:233], v[38:41]
	v_mfma_f32_16x16x32_bf16 v[46:49], v[190:193], v[230:233], v[46:49]
	s_setprio 0
	s_barrier
; #define PG8_STAGE(bufoff, gbase, voff) do { _Pragma("unroll") for (int _i = 0; _i < 2; ++_i) \
;         __builtin_amdgcn_global_load_lds((const unsigned*)((const char*)(gbase) + (voff)[_i]), (LAS unsigned*)(lds + (bufoff) + ldsw + _i * 8192), 16, 0, 0); } while (0)
; #define PG8_LDA(dst, b, h) do { _Pragma("unroll") for (int m = 0; m < 4; ++m) _Pragma("unroll") for (int k = 0; k < 2; ++k) dst[m][k] = *(const LAS bf16x8*)(lds + PG8_SA(b, h) + aoff + m * 2048 + k * 1024); } while (0)
; #define PG8_MMA(ai, bj, At, Bt) do { __builtin_amdgcn_s_setprio(1); _Pragma("unroll") for (int m = 0; m < 4; ++m) _Pragma("unroll") for (int n = 0; n < 2; ++n) _Pragma("unroll") for (int k = 0; k < 2; ++k) \
;         acc[ai][bj][m][n] = __builtin_amdgcn_mfma_f32_16x16x32_bf16(Bt[n][k], At[m][k], acc[ai][bj][m][n], 0, 0, 0); __builtin_amdgcn_s_setprio(0); } while (0)
; #define PG8_WAIT_V(n) asm volatile("s_waitcnt vmcnt(" #n ")" ::: "memory")
; #define PG8_WAIT_L(n) asm volatile("s_waitcnt lgkmcnt(" #n ")" ::: "memory")
; #define PG8_BAR __builtin_amdgcn_s_barrier()
; #define PG8_SCHED __builtin_amdgcn_sched_barrier(0)
; template <class Epi, class Sched>
; __device__ __forceinline__ void gemm_phase(LAS unsigned char* lds, const Gemm g, const Sched& S, const Epi& E) {
;     ...
;             PG8_LDA(At, 1, 1); PG8_STAGE(PG8_SB(1, 0), b3, voffB); PG8_STAGE(PG8_SB(1, 1), b3 + hstepB, voffB); PG8_STAGE(PG8_SA(1, 0), a3, voffA);
;             PG8_WAIT_V(8); PG8_WAIT_L(0); PG8_BAR; PG8_MMA(1, 0, At, B0); PG8_MMA(1, 1, At, B1); PG8_BAR; PG8_SCHED;
;         }
	s_add_i32 s20, s34, 0x18000
	s_mov_b32 m0, s20
	ds_read_b128 v[194:197], v148 offset:49152
	ds_read_b128 v[198:201], v148 offset:50176
	ds_read_b128 v[202:205], v148 offset:51200
	ds_read_b128 v[206:209], v148 offset:52224
	ds_read_b128 v[218:221], v148 offset:53248
	ds_read_b128 v[222:225], v148 offset:54272
	ds_read_b128 v[226:229], v148 offset:55296
	ds_read_b128 v[230:233], v148 offset:56320
	global_load_lds_dwordx4 v132, s[98:99]
	s_add_i32 m0, s20, 0x2000
	s_add_i32 s20, s34, 0x1c000
	global_load_lds_dwordx4 v136, s[98:99]
	s_add_u32 s98, s98, s29
	s_addc_u32 s99, s99, 0
	s_mov_b32 m0, s20
	s_nop 0
	global_load_lds_dwordx4 v132, s[98:99]
	s_add_i32 m0, s20, 0x2000
	s_nop 0
	global_load_lds_dwordx4 v136, s[98:99]
	s_mov_b32 m0, s41
	s_nop 0
	global_load_lds_dwordx4 v130, s[100:101]
	s_mov_b32 m0, s42
	s_nop 0
	global_load_lds_dwordx4 v134, s[100:101]
	s_waitcnt vmcnt(8)
	s_waitcnt lgkmcnt(0)
	s_barrier
	s_setprio 1
	s_waitcnt lgkmcnt(0)
	v_mfma_f32_16x16x32_bf16 v[14:17], v[142:145], v[194:197], v[14:17]
	v_mfma_f32_16x16x32_bf16 v[26:29], v[154:157], v[194:197], v[26:29]
	v_mfma_f32_16x16x32_bf16 v[74:77], v[142:145], v[202:205], v[74:77]
	v_mfma_f32_16x16x32_bf16 v[82:85], v[154:157], v[202:205], v[82:85]
	v_mfma_f32_16x16x32_bf16 v[42:45], v[142:145], v[218:221], v[42:45]
	v_mfma_f32_16x16x32_bf16 v[50:53], v[154:157], v[218:221], v[50:53]
	v_mfma_f32_16x16x32_bf16 v[2:5], v[142:145], v[226:229], v[2:5]
	v_mfma_f32_16x16x32_bf16 v[6:9], v[154:157], v[226:229], v[6:9]
	v_mfma_f32_16x16x32_bf16 v[14:17], v[150:153], v[198:201], v[14:17]
	v_mfma_f32_16x16x32_bf16 v[26:29], v[158:161], v[198:201], v[26:29]
	v_mfma_f32_16x16x32_bf16 v[74:77], v[150:153], v[206:209], v[74:77]
	v_mfma_f32_16x16x32_bf16 v[82:85], v[158:161], v[206:209], v[82:85]
	v_mfma_f32_16x16x32_bf16 v[42:45], v[150:153], v[222:225], v[42:45]
	v_mfma_f32_16x16x32_bf16 v[50:53], v[158:161], v[222:225], v[50:53]
	v_mfma_f32_16x16x32_bf16 v[2:5], v[150:153], v[230:233], v[2:5]
	v_mfma_f32_16x16x32_bf16 v[6:9], v[158:161], v[230:233], v[6:9]
	s_setprio 0
	s_setprio 1
	v_mfma_f32_16x16x32_bf16 v[30:33], v[162:165], v[194:197], v[30:33]
	v_mfma_f32_16x16x32_bf16 v[110:113], v[170:173], v[194:197], v[110:113]
	v_mfma_f32_16x16x32_bf16 v[86:89], v[162:165], v[202:205], v[86:89]
	v_mfma_f32_16x16x32_bf16 v[90:93], v[170:173], v[202:205], v[90:93]
	v_mfma_f32_16x16x32_bf16 v[54:57], v[162:165], v[218:221], v[54:57]
	v_mfma_f32_16x16x32_bf16 v[58:61], v[170:173], v[218:221], v[58:61]
	v_mfma_f32_16x16x32_bf16 v[10:13], v[162:165], v[226:229], v[10:13]
	v_mfma_f32_16x16x32_bf16 v[18:21], v[170:173], v[226:229], v[18:21]
	v_mfma_f32_16x16x32_bf16 v[30:33], v[166:169], v[198:201], v[30:33]
	v_mfma_f32_16x16x32_bf16 v[110:113], v[190:193], v[198:201], v[110:113]
	v_mfma_f32_16x16x32_bf16 v[86:89], v[166:169], v[206:209], v[86:89]
	v_mfma_f32_16x16x32_bf16 v[90:93], v[190:193], v[206:209], v[90:93]
	v_mfma_f32_16x16x32_bf16 v[54:57], v[166:169], v[222:225], v[54:57]
	v_mfma_f32_16x16x32_bf16 v[58:61], v[190:193], v[222:225], v[58:61]
	v_mfma_f32_16x16x32_bf16 v[10:13], v[166:169], v[230:233], v[10:13]
	v_mfma_f32_16x16x32_bf16 v[18:21], v[190:193], v[230:233], v[18:21]
	s_setprio 0
	s_barrier
	s_add_u32 s18, s18, 0x100
	s_addc_u32 s19, s19, 0
	s_add_u32 s86, s86, 0x100
	s_addc_u32 s87, s87, 0
	s_cmp_ge_u32 vcc_lo, s48
	s_mov_b32 s20, vcc_lo
	s_cbranch_scc0 .LBB0_598
	s_and_b64 vcc, exec, s[84:85]
	s_cbranch_vccz .LBB0_601
	s_barrier
